# XCC start stagger 400->200 ticks
# baseline (speedup 1.0000x reference)
.LBB0_199:
	s_xor_b64 s[0:1], s[0:1], -1
	s_and_b32 s6, s95, 7
	v_writelane_b32 v252, s0, 33
	s_and_b64 vcc, exec, s[0:1]
	s_nop 0
	v_writelane_b32 v252, s1, 34
	s_cbranch_vccnz .LBB0_203
	s_memrealtime s[0:1]
	s_memrealtime s[4:5]
	s_mul_i32 s2, s6, 0xc8
	s_mov_b32 s3, 0
	v_mov_b64_e32 v[2:3], s[2:3]
	s_waitcnt lgkmcnt(0)
	s_sub_u32 s4, s4, s0
	s_subb_u32 s5, s5, s1
	v_cmp_ge_u64_e32 vcc, s[4:5], v[2:3]
	s_cbranch_vccnz .LBB0_203
	v_mov_b64_e32 v[2:3], s[2:3]
